# gemm_out epilogue de-serialised: the 16 x loads of a tile issued together after the staging barrier, each step waits with vmcnt(15) instead of a load/vmcnt(0)/fma/store round trip
# speedup vs baseline: 1.0157x; 1.0157x over previous
; __device__ void phase_gemm_out(const Params& p, int bid, int nb, char* lds, const TileMap& tm) {
;     ...
; #pragma unroll
;     for (int j = 0; j < 2; ++j)
; #pragma unroll
;       for (int i = 0; i < 2; ++i) {
;         const int rl = 64 * wm + 32 * i + l31;
;         const float rb = rbv[rl];
; #pragma unroll
;         for (int g = 0; g < 4; ++g) {
;           const f32x16& a = acc[j][i];
;           *(float4*)(stf + rl * 132 + 64 * wn + 32 * j + 8 * g + 4 * h) = make_float4(a[4 * g] * rb, a[4 * g + 1] * rb, a[4 * g + 2] * rb, a[4 * g + 3] * rb);
;         }
;       }
;     __syncthreads();
;     const int b = m0 >> 13;
;     const float* gate = ada + b * 6144 + 2048 + n0;
;     {
;       const int c32 = tid & 31, r0 = tid >> 5;
;       const float4 gt = *(const float4*)(gate + c32 * 4);
; #pragma unroll
;       for (int q = 0; q < 16; ++q) {
;         const int row = r0 + 8 * q;
;         const size_t idx = (size_t)(m0 + row) * 1024 + n0 + c32 * 4;
;         const float4 xv = *(const float4*)(p.x + idx);
;         const float4 mv = *(const float4*)(stf + row * 132 + c32 * 4);
;         *(float4*)(p.out + idx) = make_float4(ALPHA * xv.x + gt.x * mv.x, ALPHA * xv.y + gt.y * mv.y, ALPHA * xv.z + gt.z * mv.z, ALPHA * xv.w + gt.w * mv.w);
;       }
;     }
.LBB0_310:
	s_setprio 0
	ds_read_b32 v0, v80
	s_lshr_b32 s1, s44, 6
	s_mul_i32 s40, s1, 0x1800
	s_ashr_i32 s41, s40, 31
	s_lshl_b64 s[40:41], s[40:41], 2
	s_waitcnt lgkmcnt(0)
	v_pk_mul_f32 v[50:51], v[50:51], v[0:1] op_sel_hi:[1,0]
	v_pk_mul_f32 v[52:53], v[52:53], v[0:1] op_sel_hi:[1,0]
	v_pk_mul_f32 v[54:55], v[54:55], v[0:1] op_sel_hi:[1,0]
	v_pk_mul_f32 v[56:57], v[56:57], v[0:1] op_sel_hi:[1,0]
	ds_write_b128 v82, v[50:53]
	ds_write_b128 v82, v[54:57] offset:32
	v_pk_mul_f32 v[50:51], v[58:59], v[0:1] op_sel_hi:[1,0]
	v_pk_mul_f32 v[52:53], v[60:61], v[0:1] op_sel_hi:[1,0]
	ds_write_b128 v82, v[50:53] offset:64
	v_pk_mul_f32 v[50:51], v[62:63], v[0:1] op_sel_hi:[1,0]
	v_pk_mul_f32 v[52:53], v[64:65], v[0:1] op_sel_hi:[1,0]
	ds_write_b128 v82, v[50:53] offset:96
	ds_read_b32 v0, v81
	s_add_u32 s42, s92, s40
	s_addc_u32 s43, s93, s41
	s_ashr_i32 s1, s0, 31
	s_lshl_b64 s[40:41], s[0:1], 2
	s_waitcnt lgkmcnt(0)
	v_pk_mul_f32 v[34:35], v[34:35], v[0:1] op_sel_hi:[1,0]
	v_pk_mul_f32 v[36:37], v[36:37], v[0:1] op_sel_hi:[1,0]
	ds_write_b128 v82, v[34:37] offset:16896
	v_pk_mul_f32 v[34:35], v[38:39], v[0:1] op_sel_hi:[1,0]
	v_pk_mul_f32 v[36:37], v[40:41], v[0:1] op_sel_hi:[1,0]
	ds_write_b128 v82, v[34:37] offset:16928
	v_pk_mul_f32 v[34:35], v[42:43], v[0:1] op_sel_hi:[1,0]
	v_pk_mul_f32 v[36:37], v[44:45], v[0:1] op_sel_hi:[1,0]
	ds_write_b128 v82, v[34:37] offset:16960
	v_pk_mul_f32 v[34:35], v[46:47], v[0:1] op_sel_hi:[1,0]
	v_pk_mul_f32 v[36:37], v[48:49], v[0:1] op_sel_hi:[1,0]
	ds_write_b128 v82, v[34:37] offset:16992
	ds_read_b32 v0, v80
	s_add_u32 s40, s42, s40
	s_addc_u32 s41, s43, s41
	s_add_i32 s21, s21, 1
	s_waitcnt lgkmcnt(0)
	v_pk_mul_f32 v[18:19], v[18:19], v[0:1] op_sel_hi:[1,0]
	v_pk_mul_f32 v[20:21], v[20:21], v[0:1] op_sel_hi:[1,0]
	ds_write_b128 v82, v[18:21] offset:128
	v_pk_mul_f32 v[18:19], v[22:23], v[0:1] op_sel_hi:[1,0]
	v_pk_mul_f32 v[20:21], v[24:25], v[0:1] op_sel_hi:[1,0]
	ds_write_b128 v82, v[18:21] offset:160
	v_pk_mul_f32 v[18:19], v[26:27], v[0:1] op_sel_hi:[1,0]
	v_pk_mul_f32 v[20:21], v[28:29], v[0:1] op_sel_hi:[1,0]
	ds_write_b128 v82, v[18:21] offset:192
	v_pk_mul_f32 v[18:19], v[30:31], v[0:1] op_sel_hi:[1,0]
	v_pk_mul_f32 v[20:21], v[32:33], v[0:1] op_sel_hi:[1,0]
	ds_write_b128 v82, v[18:21] offset:224
	ds_read_b32 v0, v81
	s_waitcnt lgkmcnt(0)
	v_pk_mul_f32 v[2:3], v[2:3], v[0:1] op_sel_hi:[1,0]
	v_pk_mul_f32 v[4:5], v[4:5], v[0:1] op_sel_hi:[1,0]
	ds_write_b128 v82, v[2:5] offset:17024
	v_pk_mul_f32 v[2:3], v[6:7], v[0:1] op_sel_hi:[1,0]
	v_pk_mul_f32 v[4:5], v[8:9], v[0:1] op_sel_hi:[1,0]
	ds_write_b128 v82, v[2:5] offset:17056
	v_pk_mul_f32 v[2:3], v[10:11], v[0:1] op_sel_hi:[1,0]
	v_pk_mul_f32 v[4:5], v[12:13], v[0:1] op_sel_hi:[1,0]
	v_add_u32_e32 v8, s45, v79
	ds_write_b128 v82, v[2:5] offset:17088
	v_pk_mul_f32 v[2:3], v[14:15], v[0:1] op_sel_hi:[1,0]
	v_pk_mul_f32 v[4:5], v[16:17], v[0:1] op_sel_hi:[1,0]
	v_lshlrev_b32_e32 v0, 2, v66
	v_ashrrev_i32_e32 v9, 31, v8
	ds_write_b128 v82, v[2:5] offset:17120
	v_lshl_add_u64 v[2:3], s[40:41], 0, v[0:1]
	v_mov_b32_e32 v7, s1
	v_or_b32_e32 v6, s0, v66
	v_lshlrev_b64 v[4:5], 10, v[8:9]
	s_movk_i32 s0, 0x2000
	v_lshl_add_u64 v[4:5], v[4:5], 0, v[6:7]
	v_add_co_u32_e32 v2, vcc, s0, v2
	v_lshlrev_b64 v[18:19], 2, v[4:5]
	s_nop 0
	v_addc_co_u32_e32 v3, vcc, 0, v3, vcc
	s_waitcnt lgkmcnt(0)
	s_barrier
	global_load_dwordx4 v[2:5], v[2:3], off
	v_mov_b32_e32 v248, v18
	global_load_dwordx4 v[184:187], v248, s[72:73]
	v_add_u32_e32 v248, 0x8000, v248
	global_load_dwordx4 v[188:191], v248, s[72:73]
	v_add_u32_e32 v248, 0x8000, v248
	global_load_dwordx4 v[192:195], v248, s[72:73]
	v_add_u32_e32 v248, 0x8000, v248
	global_load_dwordx4 v[196:199], v248, s[72:73]
	v_add_u32_e32 v248, 0x8000, v248
	global_load_dwordx4 v[200:203], v248, s[72:73]
	v_add_u32_e32 v248, 0x8000, v248
	global_load_dwordx4 v[204:207], v248, s[72:73]
	v_add_u32_e32 v248, 0x8000, v248
	global_load_dwordx4 v[208:211], v248, s[72:73]
	v_add_u32_e32 v248, 0x8000, v248
	global_load_dwordx4 v[212:215], v248, s[72:73]
	v_add_u32_e32 v248, 0x8000, v248
	global_load_dwordx4 v[216:219], v248, s[72:73]
	v_add_u32_e32 v248, 0x8000, v248
	global_load_dwordx4 v[220:223], v248, s[72:73]
	v_add_u32_e32 v248, 0x8000, v248
	global_load_dwordx4 v[224:227], v248, s[72:73]
	v_add_u32_e32 v248, 0x8000, v248
	global_load_dwordx4 v[228:231], v248, s[72:73]
	v_add_u32_e32 v248, 0x8000, v248
	global_load_dwordx4 v[232:235], v248, s[72:73]
	v_add_u32_e32 v248, 0x8000, v248
	global_load_dwordx4 v[236:239], v248, s[72:73]
	v_add_u32_e32 v248, 0x8000, v248
	global_load_dwordx4 v[240:243], v248, s[72:73]
	v_add_u32_e32 v248, 0x8000, v248
	global_load_dwordx4 v[244:247], v248, s[72:73]
	v_lshl_add_u64 v[10:11], s[72:73], 0, v[18:19]
	v_add_u32_e32 v14, 8, v8
	v_ashrrev_i32_e32 v15, 31, v14
	v_lshlrev_b64 v[14:15], 10, v[14:15]
	v_lshl_add_u64 v[20:21], v[14:15], 0, v[6:7]
	ds_read_b128 v[14:17], v83
	v_lshlrev_b64 v[22:23], 2, v[20:21]
	v_lshl_add_u64 v[24:25], s[90:91], 0, v[18:19]
	ds_read_b128 v[18:21], v83 offset:4224
	v_lshl_add_u64 v[26:27], s[72:73], 0, v[22:23]
	s_mov_b64 s[40:41], 0
	s_waitcnt vmcnt(16) lgkmcnt(1)
	v_pk_mul_f32 v[14:15], v[2:3], v[14:15]
	v_pk_mul_f32 v[16:17], v[4:5], v[16:17]
	s_waitcnt vmcnt(15)
	v_pk_fma_f32 v[10:11], v[184:185], s[34:35], v[14:15] op_sel_hi:[1,0,1]
	v_pk_fma_f32 v[12:13], v[186:187], s[34:35], v[16:17] op_sel_hi:[1,0,1]
	global_store_dwordx4 v[24:25], v[10:13], off
	v_add_u32_e32 v14, 16, v8
	v_ashrrev_i32_e32 v15, 31, v14
	v_lshlrev_b64 v[14:15], 10, v[14:15]
	v_lshl_add_u64 v[14:15], v[14:15], 0, v[6:7]
	s_waitcnt lgkmcnt(0)
; __device__ void phase_gemm_out(const Params& p, int bid, int nb, char* lds, const TileMap& tm) {
;     ...
; #pragma unroll
;       for (int q = 0; q < 16; ++q) {
;         const int row = r0 + 8 * q;
;         const size_t idx = (size_t)(m0 + row) * 1024 + n0 + c32 * 4;
;         const float4 xv = *(const float4*)(p.x + idx);
;         const float4 mv = *(const float4*)(stf + row * 132 + c32 * 4);
;         *(float4*)(p.out + idx) = make_float4(ALPHA * xv.x + gt.x * mv.x, ALPHA * xv.y + gt.y * mv.y, ALPHA * xv.z + gt.z * mv.z, ALPHA * xv.w + gt.w * mv.w);
;       }
	v_pk_mul_f32 v[18:19], v[2:3], v[18:19]
	v_pk_mul_f32 v[20:21], v[4:5], v[20:21]
	v_lshlrev_b64 v[24:25], 2, v[14:15]
	v_lshl_add_u64 v[14:15], s[90:91], 0, v[22:23]
	v_lshl_add_u64 v[16:17], s[72:73], 0, v[24:25]
	v_lshl_add_u64 v[24:25], s[90:91], 0, v[24:25]
	s_waitcnt vmcnt(15)
	v_pk_fma_f32 v[10:11], v[188:189], s[34:35], v[18:19] op_sel_hi:[1,0,1]
	v_pk_fma_f32 v[12:13], v[190:191], s[34:35], v[20:21] op_sel_hi:[1,0,1]
	global_store_dwordx4 v[14:15], v[10:13], off
	v_add_u32_e32 v14, 24, v8
	v_ashrrev_i32_e32 v15, 31, v14
	v_lshlrev_b64 v[14:15], 10, v[14:15]
	v_lshl_add_u64 v[18:19], v[14:15], 0, v[6:7]
	ds_read_b128 v[14:17], v83 offset:8448
	v_lshlrev_b64 v[22:23], 2, v[18:19]
	ds_read_b128 v[18:21], v83 offset:12672
	v_lshl_add_u64 v[26:27], s[72:73], 0, v[22:23]
	s_waitcnt lgkmcnt(1)
	v_pk_mul_f32 v[14:15], v[2:3], v[14:15]
	v_pk_mul_f32 v[16:17], v[4:5], v[16:17]
	s_waitcnt lgkmcnt(0)
	v_pk_mul_f32 v[18:19], v[2:3], v[18:19]
	v_pk_mul_f32 v[20:21], v[4:5], v[20:21]
	s_waitcnt vmcnt(15)
	v_pk_fma_f32 v[10:11], v[192:193], s[34:35], v[14:15] op_sel_hi:[1,0,1]
	v_pk_fma_f32 v[12:13], v[194:195], s[34:35], v[16:17] op_sel_hi:[1,0,1]
	global_store_dwordx4 v[24:25], v[10:13], off
	v_add_u32_e32 v14, 32, v8
	v_ashrrev_i32_e32 v15, 31, v14
	v_lshlrev_b64 v[14:15], 10, v[14:15]
	v_lshl_add_u64 v[14:15], v[14:15], 0, v[6:7]
	v_lshlrev_b64 v[24:25], 2, v[14:15]
	v_lshl_add_u64 v[14:15], s[90:91], 0, v[22:23]
	v_lshl_add_u64 v[16:17], s[72:73], 0, v[24:25]
	v_lshl_add_u64 v[24:25], s[90:91], 0, v[24:25]
	s_waitcnt vmcnt(15)
	v_pk_fma_f32 v[10:11], v[196:197], s[34:35], v[18:19] op_sel_hi:[1,0,1]
	v_pk_fma_f32 v[12:13], v[198:199], s[34:35], v[20:21] op_sel_hi:[1,0,1]
	global_store_dwordx4 v[14:15], v[10:13], off
	v_add_u32_e32 v14, 40, v8
	v_ashrrev_i32_e32 v15, 31, v14
	v_lshlrev_b64 v[14:15], 10, v[14:15]
	v_lshl_add_u64 v[18:19], v[14:15], 0, v[6:7]
	ds_read_b128 v[14:17], v83 offset:16896
	v_lshlrev_b64 v[22:23], 2, v[18:19]
	ds_read_b128 v[18:21], v83 offset:21120
	v_lshl_add_u64 v[26:27], s[72:73], 0, v[22:23]
	s_waitcnt lgkmcnt(1)
	v_pk_mul_f32 v[14:15], v[2:3], v[14:15]
	v_pk_mul_f32 v[16:17], v[4:5], v[16:17]
	s_waitcnt lgkmcnt(0)
	v_pk_mul_f32 v[18:19], v[2:3], v[18:19]
	v_pk_mul_f32 v[20:21], v[4:5], v[20:21]
	s_waitcnt vmcnt(15)
	v_pk_fma_f32 v[10:11], v[200:201], s[34:35], v[14:15] op_sel_hi:[1,0,1]
	v_pk_fma_f32 v[12:13], v[202:203], s[34:35], v[16:17] op_sel_hi:[1,0,1]
	global_store_dwordx4 v[24:25], v[10:13], off
	v_add_u32_e32 v14, 48, v8
	v_ashrrev_i32_e32 v15, 31, v14
	v_lshlrev_b64 v[14:15], 10, v[14:15]
	v_lshl_add_u64 v[14:15], v[14:15], 0, v[6:7]
	v_lshlrev_b64 v[24:25], 2, v[14:15]
	v_lshl_add_u64 v[14:15], s[90:91], 0, v[22:23]
	v_lshl_add_u64 v[16:17], s[72:73], 0, v[24:25]
	v_lshl_add_u64 v[24:25], s[90:91], 0, v[24:25]
	s_waitcnt vmcnt(15)
	v_pk_fma_f32 v[10:11], v[204:205], s[34:35], v[18:19] op_sel_hi:[1,0,1]
	v_pk_fma_f32 v[12:13], v[206:207], s[34:35], v[20:21] op_sel_hi:[1,0,1]
	global_store_dwordx4 v[14:15], v[10:13], off
	v_add_u32_e32 v14, 56, v8
	v_ashrrev_i32_e32 v15, 31, v14
	v_lshlrev_b64 v[14:15], 10, v[14:15]
	v_lshl_add_u64 v[18:19], v[14:15], 0, v[6:7]
	ds_read_b128 v[14:17], v83 offset:25344
	v_lshlrev_b64 v[22:23], 2, v[18:19]
	ds_read_b128 v[18:21], v83 offset:29568
	v_lshl_add_u64 v[26:27], s[72:73], 0, v[22:23]
	s_waitcnt lgkmcnt(1)
	v_pk_mul_f32 v[14:15], v[2:3], v[14:15]
	v_pk_mul_f32 v[16:17], v[4:5], v[16:17]
	s_waitcnt lgkmcnt(0)
	v_pk_mul_f32 v[18:19], v[2:3], v[18:19]
	v_pk_mul_f32 v[20:21], v[4:5], v[20:21]
	s_waitcnt vmcnt(15)
	v_pk_fma_f32 v[10:11], v[208:209], s[34:35], v[14:15] op_sel_hi:[1,0,1]
	v_pk_fma_f32 v[12:13], v[210:211], s[34:35], v[16:17] op_sel_hi:[1,0,1]
	global_store_dwordx4 v[24:25], v[10:13], off
	v_add_u32_e32 v14, 64, v8
	v_ashrrev_i32_e32 v15, 31, v14
	v_lshlrev_b64 v[14:15], 10, v[14:15]
	v_lshl_add_u64 v[14:15], v[14:15], 0, v[6:7]
	v_lshlrev_b64 v[24:25], 2, v[14:15]
	v_lshl_add_u64 v[14:15], s[90:91], 0, v[22:23]
	v_lshl_add_u64 v[16:17], s[72:73], 0, v[24:25]
	v_lshl_add_u64 v[24:25], s[90:91], 0, v[24:25]
	s_waitcnt vmcnt(15)
	v_pk_fma_f32 v[10:11], v[212:213], s[34:35], v[18:19] op_sel_hi:[1,0,1]
	v_pk_fma_f32 v[12:13], v[214:215], s[34:35], v[20:21] op_sel_hi:[1,0,1]
	global_store_dwordx4 v[14:15], v[10:13], off
	v_add_u32_e32 v14, 0x48, v8
	v_ashrrev_i32_e32 v15, 31, v14
	v_lshlrev_b64 v[14:15], 10, v[14:15]
	v_lshl_add_u64 v[18:19], v[14:15], 0, v[6:7]
	ds_read_b128 v[14:17], v83 offset:33792
	v_lshlrev_b64 v[22:23], 2, v[18:19]
	ds_read_b128 v[18:21], v83 offset:38016
	v_lshl_add_u64 v[26:27], s[72:73], 0, v[22:23]
	s_waitcnt lgkmcnt(1)
; __device__ void phase_gemm_out(const Params& p, int bid, int nb, char* lds, const TileMap& tm) {
;     ...
; #pragma unroll
;       for (int q = 0; q < 16; ++q) {
;         const int row = r0 + 8 * q;
;         const size_t idx = (size_t)(m0 + row) * 1024 + n0 + c32 * 4;
;         const float4 xv = *(const float4*)(p.x + idx);
;         const float4 mv = *(const float4*)(stf + row * 132 + c32 * 4);
;         *(float4*)(p.out + idx) = make_float4(ALPHA * xv.x + gt.x * mv.x, ALPHA * xv.y + gt.y * mv.y, ALPHA * xv.z + gt.z * mv.z, ALPHA * xv.w + gt.w * mv.w);
;       }
;     }
;     __syncthreads();
	v_pk_mul_f32 v[14:15], v[2:3], v[14:15]
	v_pk_mul_f32 v[16:17], v[4:5], v[16:17]
	s_waitcnt lgkmcnt(0)
	v_pk_mul_f32 v[18:19], v[2:3], v[18:19]
	v_pk_mul_f32 v[20:21], v[4:5], v[20:21]
	s_waitcnt vmcnt(15)
	v_pk_fma_f32 v[10:11], v[216:217], s[34:35], v[14:15] op_sel_hi:[1,0,1]
	v_pk_fma_f32 v[12:13], v[218:219], s[34:35], v[16:17] op_sel_hi:[1,0,1]
	global_store_dwordx4 v[24:25], v[10:13], off
	v_add_u32_e32 v14, 0x50, v8
	v_ashrrev_i32_e32 v15, 31, v14
	v_lshlrev_b64 v[14:15], 10, v[14:15]
	v_lshl_add_u64 v[14:15], v[14:15], 0, v[6:7]
	v_lshlrev_b64 v[24:25], 2, v[14:15]
	v_lshl_add_u64 v[14:15], s[90:91], 0, v[22:23]
	v_lshl_add_u64 v[16:17], s[72:73], 0, v[24:25]
	v_lshl_add_u64 v[24:25], s[90:91], 0, v[24:25]
	s_waitcnt vmcnt(15)
	v_pk_fma_f32 v[10:11], v[220:221], s[34:35], v[18:19] op_sel_hi:[1,0,1]
	v_pk_fma_f32 v[12:13], v[222:223], s[34:35], v[20:21] op_sel_hi:[1,0,1]
	global_store_dwordx4 v[14:15], v[10:13], off
	v_add_u32_e32 v14, 0x58, v8
	v_ashrrev_i32_e32 v15, 31, v14
	v_lshlrev_b64 v[14:15], 10, v[14:15]
	v_lshl_add_u64 v[18:19], v[14:15], 0, v[6:7]
	ds_read_b128 v[14:17], v83 offset:42240
	v_lshlrev_b64 v[22:23], 2, v[18:19]
	ds_read_b128 v[18:21], v83 offset:46464
	v_lshl_add_u64 v[26:27], s[72:73], 0, v[22:23]
	s_waitcnt lgkmcnt(1)
	v_pk_mul_f32 v[14:15], v[2:3], v[14:15]
	v_pk_mul_f32 v[16:17], v[4:5], v[16:17]
	s_waitcnt lgkmcnt(0)
	v_pk_mul_f32 v[18:19], v[2:3], v[18:19]
	v_pk_mul_f32 v[20:21], v[4:5], v[20:21]
	s_waitcnt vmcnt(15)
	v_pk_fma_f32 v[10:11], v[224:225], s[34:35], v[14:15] op_sel_hi:[1,0,1]
	v_pk_fma_f32 v[12:13], v[226:227], s[34:35], v[16:17] op_sel_hi:[1,0,1]
	global_store_dwordx4 v[24:25], v[10:13], off
	v_add_u32_e32 v14, 0x60, v8
	v_ashrrev_i32_e32 v15, 31, v14
	v_lshlrev_b64 v[14:15], 10, v[14:15]
	v_lshl_add_u64 v[14:15], v[14:15], 0, v[6:7]
	v_lshlrev_b64 v[24:25], 2, v[14:15]
	v_lshl_add_u64 v[14:15], s[90:91], 0, v[22:23]
	v_lshl_add_u64 v[16:17], s[72:73], 0, v[24:25]
	v_lshl_add_u64 v[24:25], s[90:91], 0, v[24:25]
	s_waitcnt vmcnt(15)
	v_pk_fma_f32 v[10:11], v[228:229], s[34:35], v[18:19] op_sel_hi:[1,0,1]
	v_pk_fma_f32 v[12:13], v[230:231], s[34:35], v[20:21] op_sel_hi:[1,0,1]
	global_store_dwordx4 v[14:15], v[10:13], off
	v_add_u32_e32 v14, 0x68, v8
	v_ashrrev_i32_e32 v15, 31, v14
	v_lshlrev_b64 v[14:15], 10, v[14:15]
	v_lshl_add_u64 v[18:19], v[14:15], 0, v[6:7]
	ds_read_b128 v[14:17], v83 offset:50688
	v_lshlrev_b64 v[22:23], 2, v[18:19]
	ds_read_b128 v[18:21], v83 offset:54912
	v_lshl_add_u64 v[26:27], s[72:73], 0, v[22:23]
	s_waitcnt lgkmcnt(1)
	v_pk_mul_f32 v[14:15], v[2:3], v[14:15]
	v_pk_mul_f32 v[16:17], v[4:5], v[16:17]
	s_waitcnt lgkmcnt(0)
	v_pk_mul_f32 v[18:19], v[2:3], v[18:19]
	v_pk_mul_f32 v[20:21], v[4:5], v[20:21]
	s_waitcnt vmcnt(15)
	v_pk_fma_f32 v[10:11], v[232:233], s[34:35], v[14:15] op_sel_hi:[1,0,1]
	v_pk_fma_f32 v[12:13], v[234:235], s[34:35], v[16:17] op_sel_hi:[1,0,1]
	global_store_dwordx4 v[24:25], v[10:13], off
	v_add_u32_e32 v14, 0x70, v8
	v_ashrrev_i32_e32 v15, 31, v14
	v_lshlrev_b64 v[14:15], 10, v[14:15]
	v_lshl_add_u64 v[14:15], v[14:15], 0, v[6:7]
	v_lshlrev_b64 v[14:15], 2, v[14:15]
	v_lshl_add_u64 v[16:17], s[90:91], 0, v[22:23]
	v_lshl_add_u64 v[22:23], s[72:73], 0, v[14:15]
	v_add_u32_e32 v8, 0x78, v8
	v_ashrrev_i32_e32 v9, 31, v8
	v_lshlrev_b64 v[8:9], 10, v[8:9]
	s_waitcnt vmcnt(15)
	v_pk_fma_f32 v[10:11], v[236:237], s[34:35], v[18:19] op_sel_hi:[1,0,1]
	v_pk_fma_f32 v[12:13], v[238:239], s[34:35], v[20:21] op_sel_hi:[1,0,1]
	global_store_dwordx4 v[16:17], v[10:13], off
	v_lshl_add_u64 v[16:17], v[8:9], 0, v[6:7]
	ds_read_b128 v[6:9], v83 offset:59136
	v_lshlrev_b64 v[18:19], 2, v[16:17]
	v_lshl_add_u64 v[20:21], s[90:91], 0, v[14:15]
	ds_read_b128 v[14:17], v83 offset:63360
	v_lshl_add_u64 v[22:23], s[72:73], 0, v[18:19]
	s_waitcnt lgkmcnt(1)
	v_pk_mul_f32 v[6:7], v[2:3], v[6:7]
	v_pk_mul_f32 v[8:9], v[4:5], v[8:9]
	s_waitcnt lgkmcnt(0)
	v_pk_mul_f32 v[2:3], v[2:3], v[14:15]
	v_pk_mul_f32 v[4:5], v[4:5], v[16:17]
	s_waitcnt vmcnt(15)
	v_pk_fma_f32 v[6:7], v[240:241], s[34:35], v[6:7] op_sel_hi:[1,0,1]
	v_pk_fma_f32 v[8:9], v[242:243], s[34:35], v[8:9] op_sel_hi:[1,0,1]
	global_store_dwordx4 v[20:21], v[6:9], off
	v_lshl_add_u64 v[10:11], s[90:91], 0, v[18:19]
	s_waitcnt vmcnt(15)
	v_pk_fma_f32 v[2:3], v[244:245], s[34:35], v[2:3] op_sel_hi:[1,0,1]
	v_pk_fma_f32 v[4:5], v[246:247], s[34:35], v[4:5] op_sel_hi:[1,0,1]
	global_store_dwordx4 v[10:11], v[2:5], off
	s_barrier
